# attention: waves 4-7 staggered (softmax+PV of previous tile before QK of current tile); gdn producer 2-deep register double buffer
# speedup vs baseline: 1.0336x; 1.0082x over previous
; #define LAS __attribute__((address_space(3)))
; __device__ __forceinline__ void attn_phase(const Ctx& c, const Params& p, int o, int first, int cidx) {
;     ...
;         bf16x8 qf[6]; { const bf16_t* qp = QH + (size_t)(b * T_ + qs + l31) * 768 + h * 96 + 8 * hh;
; #pragma unroll
;             for (int ks = 0; ks < 6; ++ks) qf[ks] = *(const bf16x8*)(qp + 16 * ks); }
;         f32x16 o0 = {}, o1 = {}; float mrun = -INFINITY, lrun = 0.f;
;         const int ntile = 4 * (qblk + 1);
;         const bf16_t* kg = KH + (size_t)(b * T_) * 768 + h * 96; const bf16_t* vg = VT + (size_t)bh * 64 * T_;
;         u32x4 rk0, rk1 = {}, rv;
;         rk0 = *(const u32x4*)(kg + (size_t)k0row * 768 + 8 * k0ch); if (k1on) rk1 = *(const u32x4*)(kg + (size_t)k1row * 768 + 8 * k1ch); rv = *(const u32x4*)(vg + (size_t)vrow * T_ + 8 * vch);
;         *(LAS u32x4*)(sK + k0row * 104 + 8 * k0ch) = rk0; if (k1on) *(LAS u32x4*)(sK + k1row * 104 + 8 * k1ch) = rk1; *(LAS u32x4*)(sVt + vrow * 72 + 8 * vch) = rv;
;         __syncthreads();
;         for (int kt = 0; kt < ntile; ++kt) { const int kv0 = kt * 64; const int buf = kt & 1;
.LBB0_117:
	s_or_b64 exec, exec, s[18:19]
	s_lshl_b32 s11, s11, 20
	s_and_b32 s42, s11, 0x1f00000
	v_lshl_add_u64 v[118:119], v[114:115], 0, s[42:43]
	global_load_dwordx4 v[98:101], v[118:119], off
	s_waitcnt vmcnt(0) lgkmcnt(0)
	ds_write_b128 v126, v[90:93]
	s_and_saveexec_b64 s[18:19], s[6:7]
	ds_write_b128 v134, v[94:97]
	s_or_b64 exec, exec, s[18:19]
	v_mov_b32_e32 v14, v0
	v_mov_b32_e32 v15, v0
	v_mov_b32_e32 v1, v0
	v_mov_b32_e32 v2, v0
	v_mov_b32_e32 v3, v0
	v_mov_b32_e32 v4, v0
	v_mov_b32_e32 v5, v0
	v_mov_b32_e32 v6, v0
	v_mov_b32_e32 v7, v0
	v_mov_b32_e32 v8, v0
	v_mov_b32_e32 v9, v0
	v_mov_b32_e32 v10, v0
	v_mov_b32_e32 v11, v0
	v_mov_b32_e32 v12, v0
	v_mov_b32_e32 v13, v0
	v_mov_b64_e32 v[32:33], v[14:15]
	s_lshl_b32 s10, s10, 2
	s_mov_b32 s42, 0
	v_mov_b64_e32 v[30:31], v[12:13]
	v_mov_b64_e32 v[28:29], v[10:11]
	v_mov_b64_e32 v[26:27], v[8:9]
	v_mov_b64_e32 v[24:25], v[6:7]
	v_mov_b64_e32 v[22:23], v[4:5]
	v_mov_b64_e32 v[20:21], v[2:3]
	v_mov_b64_e32 v[18:19], v[0:1]
	v_mov_b64_e32 v[16:17], v[14:15]
	v_ashrrev_i32_e32 v117, 31, v116
	s_sub_i32 s27, 0x80, s10
	v_lshl_add_u64 v[120:121], v[106:107], 1, s[2:3]
	v_lshl_add_u64 v[122:123], v[110:111], 1, s[2:3]
	s_addk_i32 s29, 0x1f1f
	v_or_b32_e32 v135, s26, v124
	v_mov_b32_e32 v136, 0
	v_mov_b32_e32 v137, 0xff800000
	v_mov_b64_e32 v[14:15], v[12:13]
	v_mov_b64_e32 v[12:13], v[10:11]
	v_mov_b64_e32 v[10:11], v[8:9]
	v_mov_b64_e32 v[8:9], v[6:7]
	v_mov_b64_e32 v[6:7], v[4:5]
	v_mov_b64_e32 v[4:5], v[2:3]
	v_mov_b64_e32 v[2:3], v[0:1]
	s_mov_b32 s10, s42
	ds_write_b128 v129, v[98:101] offset:26624
	s_waitcnt lgkmcnt(0)
	s_barrier
	v_readlane_b32 s11, v255, 5
	s_cmp_ge_u32 s11, 4
	s_cbranch_scc1 .Lsb_loop

; __device__ __forceinline__ void attn_phase(const Ctx& c, const Params& p, int o, int first, int cidx) {
;     ...
;         for (int kt = 0; kt < ntile; ++kt) { const int kv0 = kt * 64; const int buf = kt & 1;
;             if (kt + 1 < ntile) { const int kn = kv0 + 64;
;                 rk0 = *(const u32x4*)(kg + (size_t)(kn + k0row) * 768 + 8 * k0ch); if (k1on) rk1 = *(const u32x4*)(kg + (size_t)(kn + k1row) * 768 + 8 * k1ch); rv = *(const u32x4*)(vg + (size_t)vrow * T_ + kn + 8 * vch); }
;             if (kv0 <= qs + 31) {
.Lsb_loop:
	s_add_i32 s31, s10, 1
	s_cmp_lt_u32 s31, s27
	s_cselect_b64 s[2:3], -1, 0
	s_cmp_ge_u32 s31, s27
	s_cbranch_scc1 .Lsb_124
	v_add_u32_e32 v250, s42, v133
	v_mad_i64_i32 v[248:249], s[18:19], v250, s50, v[120:121]
	s_waitcnt vmcnt(0)
	global_load_dwordx4 v[90:93], v[248:249], off
	s_and_saveexec_b64 s[18:19], s[6:7]
	s_cbranch_execz .Lsb_123
	v_add_u32_e32 v250, s42, v132
	v_mad_i64_i32 v[248:249], s[34:35], v250, s50, v[122:123]
	global_load_dwordx4 v[94:97], v[248:249], off
.Lsb_123:
	s_or_b64 exec, exec, s[18:19]
	v_lshl_add_u64 v[248:249], s[42:43], 1, v[118:119]
	global_load_dwordx4 v[98:101], v[248:249], off offset:128
.Lsb_124:
	s_and_b32 s18, s10, 1
	s_cmp_eq_u32 s10, 0
	s_cbranch_scc1 .Lsb_nosm
	s_sub_i32 s11, s42, 64
	s_cmp_gt_i32 s11, s29
	s_cbranch_scc1 .Lsb_nosm

; #define PV_STEP(OACC, mm, ktt, ss, PF) do { OACC = __builtin_amdgcn_mfma_f32_32x32x16_bf16(ldA_perm(vb + (mm) * 32 * 72 + 32 * (ktt) + 16 * (ss)), PF, OACC, 0, 0, 0); } while (0)
; __device__ __forceinline__ void attn_phase(const Ctx& c, const Params& p, int o, int first, int cidx) {
;     ...
;                 const float mnew = fmaxf(mrun, mx);
;                 if (__any(mnew > mrun)) { const float alpha = __builtin_amdgcn_exp2f(mrun - mnew); lrun *= alpha; o0 = o0 * alpha; o1 = o1 * alpha; }
;                 mrun = mnew;
;                 f32x16 e0, e1;
; #pragma unroll
;                 for (int r = 0; r < 16; ++r) { e0[r] = __builtin_amdgcn_exp2f(p0[r] - mnew); e1[r] = __builtin_amdgcn_exp2f(p1[r] - mnew); }
;                 p0 = e0; p1 = e1;
;                 { const f32x16 t = e0 + e1; lrun += ((t[0] + t[1]) + (t[2] + t[3])) + ((t[4] + t[5]) + (t[6] + t[7])) + ((t[8] + t[9]) + (t[10] + t[11])) + ((t[12] + t[13]) + (t[14] + t[15])); }
;                 const bf16x8 pf00 = pkfrag(p0, 0), pf01 = pkfrag(p0, 1), pf10 = pkfrag(p1, 0), pf11 = pkfrag(p1, 1);
;     ...
;                 PV_STEP(o0, 0, 0, 0, pf00); PV_STEP(o0, 0, 0, 1, pf01); PV_STEP(o0, 0, 1, 0, pf10); PV_STEP(o0, 0, 1, 1, pf11);
;                 PV_STEP(o1, 1, 0, 0, pf00); PV_STEP(o1, 1, 0, 1, pf01); PV_STEP(o1, 1, 1, 0, pf10); PV_STEP(o1, 1, 1, 1, pf11);
.Lsb_129:
	v_sub_f32_e32 v38, v38, v1
	v_exp_f32_e32 v138, v38
	v_sub_f32_e32 v38, v55, v1
	v_exp_f32_e32 v55, v38
	v_sub_f32_e32 v38, v39, v1
	v_sub_f32_e32 v39, v40, v1
	v_sub_f32_e32 v40, v41, v1
	v_sub_f32_e32 v41, v42, v1
	v_sub_f32_e32 v42, v43, v1
	v_exp_f32_e32 v139, v38
	v_sub_f32_e32 v38, v56, v1
	v_exp_f32_e32 v56, v39
	v_sub_f32_e32 v39, v57, v1
	v_exp_f32_e32 v57, v40
	v_sub_f32_e32 v40, v58, v1
	v_exp_f32_e32 v58, v41
	v_sub_f32_e32 v41, v59, v1
	v_exp_f32_e32 v59, v42
	v_sub_f32_e32 v42, v60, v1
	v_exp_f32_e32 v60, v42
	v_sub_f32_e32 v42, v44, v1
	v_exp_f32_e32 v140, v42
	v_sub_f32_e32 v42, v61, v1
	v_exp_f32_e32 v61, v42
	v_sub_f32_e32 v42, v45, v1
	v_exp_f32_e32 v141, v42
	v_sub_f32_e32 v42, v62, v1
	v_exp_f32_e32 v44, v42
	v_sub_f32_e32 v42, v46, v1
	v_exp_f32_e32 v62, v42
	v_sub_f32_e32 v42, v63, v1
	v_sub_f32_e32 v50, v50, v1
	v_sub_f32_e32 v34, v34, v1
	v_sub_f32_e32 v51, v51, v1
	v_sub_f32_e32 v35, v35, v1
	v_sub_f32_e32 v52, v52, v1
	v_sub_f32_e32 v36, v36, v1
	v_sub_f32_e32 v53, v53, v1
	v_sub_f32_e32 v37, v37, v1
	v_exp_f32_e32 v45, v42
	v_sub_f32_e32 v42, v47, v1
	v_exp_f32_e32 v50, v50
	v_exp_f32_e32 v34, v34
	v_exp_f32_e32 v51, v51
	v_exp_f32_e32 v35, v35
	v_exp_f32_e32 v52, v52
	v_exp_f32_e32 v36, v36
	v_exp_f32_e32 v53, v53
	v_exp_f32_e32 v37, v37
	v_sub_f32_e32 v54, v54, v1
	v_exp_f32_e32 v63, v42
	v_sub_f32_e32 v42, v64, v1
	v_exp_f32_e32 v54, v54
	v_exp_f32_e32 v38, v38
	v_exp_f32_e32 v39, v39
	v_exp_f32_e32 v64, v42
	v_sub_f32_e32 v42, v48, v1
	v_exp_f32_e32 v142, v42
	v_sub_f32_e32 v42, v65, v1
	v_exp_f32_e32 v65, v42
	v_sub_f32_e32 v42, v49, v1
	v_exp_f32_e32 v40, v40
	v_exp_f32_e32 v41, v41
	v_exp_f32_e32 v143, v42
	v_pk_add_f32 v[184:185], v[52:53], v[36:37]
	v_pk_add_f32 v[186:187], v[50:51], v[34:35]
	v_pk_add_f32 v[170:171], v[38:39], v[56:57]
	v_pk_add_f32 v[174:175], v[54:55], v[138:139]
	v_pk_mov_b32 v[188:189], v[186:187], v[184:185] op_sel:[1,0]
	v_mov_b32_e32 v187, v185
	v_pk_add_f32 v[184:185], v[188:189], v[186:187]
	v_pk_mov_b32 v[186:187], v[174:175], v[170:171] op_sel:[1,0]
	v_mov_b32_e32 v175, v171
	v_pk_add_f32 v[170:171], v[186:187], v[174:175]
	v_pk_add_f32 v[42:43], v[64:65], v[142:143]
	v_pk_add_f32 v[46:47], v[44:45], v[62:63]
	v_pk_add_f32 v[48:49], v[60:61], v[140:141]
	v_pk_add_f32 v[168:169], v[40:41], v[58:59]
	v_pk_add_f32 v[184:185], v[184:185], v[184:185] op_sel_hi:[0,1]
	v_pk_add_f32 v[170:171], v[170:171], v[170:171] op_sel_hi:[0,1]
	v_add_f32_e32 v169, v168, v169
	v_add_f32_e32 v49, v48, v49
	v_mov_b32_e32 v168, v46
	v_mov_b32_e32 v48, v47
	v_mov_b32_e32 v184, v42
	v_mov_b32_e32 v170, v43
	s_mul_i32 s10, s18, 0x2400
	v_pk_add_f32 v[46:47], v[168:169], v[48:49]
	v_pk_add_f32 v[42:43], v[184:185], v[170:171]
	v_cvt_pk_bf16_f32 v49, v38, v39
	v_pk_add_f32 v[42:43], v[46:47], v[42:43]
	v_cvt_pk_bf16_f32 v38, v34, v35
	v_cvt_pk_bf16_f32 v34, v58, v59
	v_add_u32_e32 v58, s10, v131
	v_add_f32_e32 v42, v42, v43
	v_add_u32_e32 v59, 0x6800, v58
	v_add_f32_e32 v136, v42, v136
	v_cvt_pk_bf16_f32 v46, v50, v51
	v_cvt_pk_bf16_f32 v47, v52, v53
	v_cvt_pk_bf16_f32 v48, v54, v55
	v_cvt_pk_bf16_f32 v42, v40, v41
	v_cvt_pk_bf16_f32 v41, v56, v57
	s_waitcnt lgkmcnt(0)
	v_mfma_f32_32x32x16_bf16 v[18:33], v[200:203], v[46:49], v[18:33]
	v_cvt_pk_bf16_f32 v43, v60, v61
	v_cvt_pk_bf16_f32 v44, v44, v45
	v_cvt_pk_bf16_f32 v45, v64, v65
	v_cvt_pk_bf16_f32 v39, v36, v37
	v_cvt_pk_bf16_f32 v40, v138, v139
	v_cvt_pk_bf16_f32 v35, v140, v141
	v_cvt_pk_bf16_f32 v36, v62, v63
	v_cvt_pk_bf16_f32 v37, v142, v143
	v_mfma_f32_32x32x16_bf16 v[2:17], v[216:219], v[46:49], v[2:17]
	v_mfma_f32_32x32x16_bf16 v[18:33], v[204:207], v[42:45], v[18:33]
	v_mfma_f32_32x32x16_bf16 v[2:17], v[220:223], v[42:45], v[2:17]
	v_mfma_f32_32x32x16_bf16 v[18:33], v[208:211], v[38:41], v[18:33]
	v_mfma_f32_32x32x16_bf16 v[2:17], v[224:227], v[38:41], v[2:17]
	v_mfma_f32_32x32x16_bf16 v[18:33], v[212:215], v[34:37], v[18:33]
	v_mfma_f32_32x32x16_bf16 v[2:17], v[228:231], v[34:37], v[2:17]
	v_mov_b32_e32 v137, v1
; #define LAS __attribute__((address_space(3)))
; __device__ __forceinline__ int crow(int r, int hi) { return (r & 3) + 8 * (r >> 2) + 4 * hi; }
; __device__ __forceinline__ void attn_phase(const Ctx& c, const Params& p, int o, int first, int cidx) {
;     ...
;         for (int kt = 0; kt < ntile; ++kt) { const int kv0 = kt * 64; const int buf = kt & 1;
;             if (kt + 1 < ntile) { const int kn = kv0 + 64;
;                 rk0 = *(const u32x4*)(kg + (size_t)(kn + k0row) * 768 + 8 * k0ch); if (k1on) rk1 = *(const u32x4*)(kg + (size_t)(kn + k1row) * 768 + 8 * k1ch); rv = *(const u32x4*)(vg + (size_t)vrow * T_ + kn + 8 * vch); }
;             if (kv0 <= qs + 31) {
;                 const LAS bf16_t* kb = sK + buf * 6656 + l31 * 104 + 8 * hh; const LAS bf16_t* vb = sVt + buf * 4608 + l31 * 72 + 4 * hh;
;                 f32x16 p0 = {}, p1 = {};
; #pragma unroll
;                 for (int ks = 0; ks < 6; ++ks) { const bf16x8 k0 = *(const LAS bf16x8*)(kb + 16 * ks); const bf16x8 k1 = *(const LAS bf16x8*)(kb + 32 * 104 + 16 * ks);
;                     p0 = __builtin_amdgcn_mfma_f32_32x32x16_bf16(k0, qf[ks], p0, 0, 0, 0); p1 = __builtin_amdgcn_mfma_f32_32x32x16_bf16(k1, qf[ks], p1, 0, 0, 0); }
;                 if (kv0 + 63 > qs) { const int q = qs + l31;
; #pragma unroll
;                     for (int r = 0; r < 16; ++r) { const int kv = kv0 + crow(r, hh); if (kv > q) p0[r] = -INFINITY; if (kv + 32 > q) p1[r] = -INFINITY; } }
;     ...
;             if (kt + 1 < ntile) { const int nb = buf ^ 1;
;                 *(LAS u32x4*)(sK + nb * 6656 + k0row * 104 + 8 * k0ch) = rk0; if (k1on) *(LAS u32x4*)(sK + nb * 6656 + k1row * 104 + 8 * k1ch) = rk1; *(LAS u32x4*)(sVt + nb * 4608 + vrow * 72 + 8 * vch) = rv; }
;             __syncthreads();
.Lsb_nosm:
	s_cmp_gt_i32 s42, s29
	s_cbranch_scc1 .Lsb_noqk
	s_mul_i32 s10, s18, 0x3400
	s_mul_i32 s11, s18, 0x2400
	v_add_u32_e32 v1, s10, v130
	v_add_u32_e32 v142, s11, v131
	ds_read_b128 v[200:203], v1
	ds_read_b128 v[204:207], v1 offset:6656
	ds_read_b128 v[208:211], v1 offset:32
	ds_read_b128 v[212:215], v1 offset:6688
	ds_read_b128 v[216:219], v1 offset:64
	ds_read_b128 v[220:223], v1 offset:6720
	ds_read_b128 v[224:227], v1 offset:96
	ds_read_b128 v[228:231], v1 offset:6752
	ds_read_b128 v[232:235], v1 offset:128
	ds_read_b128 v[236:239], v1 offset:6784
	ds_read_b128 v[240:243], v1 offset:160
	ds_read_b128 v[244:247], v1 offset:6816
	v_add_u32_e32 v143, 0x7a00, v142
	v_add_u32_e32 v142, 0x6800, v142
	s_add_i32 s10, s42, 63
	s_cmp_le_i32 s10, s26
	s_waitcnt lgkmcnt(10)
	v_mfma_f32_32x32x16_bf16 v[50:65], v[200:203], v[66:69], 0
	v_mfma_f32_32x32x16_bf16 v[34:49], v[204:207], v[66:69], 0
	ds_read2_b64 v[200:203], v142 offset1:2
	ds_read2_b64 v[204:207], v142 offset0:4 offset1:6
	s_waitcnt lgkmcnt(10)
	v_mfma_f32_32x32x16_bf16 v[50:65], v[208:211], v[70:73], v[50:65]
	v_mfma_f32_32x32x16_bf16 v[34:49], v[212:215], v[70:73], v[34:49]
	ds_read2_b64 v[208:211], v142 offset0:8 offset1:10
	ds_read2_b64 v[212:215], v142 offset0:12 offset1:14
	s_waitcnt lgkmcnt(10)
	v_mfma_f32_32x32x16_bf16 v[50:65], v[216:219], v[74:77], v[50:65]
	v_mfma_f32_32x32x16_bf16 v[34:49], v[220:223], v[74:77], v[34:49]
	ds_read2_b64 v[216:219], v143 offset1:2
	ds_read2_b64 v[220:223], v143 offset0:4 offset1:6
	s_waitcnt lgkmcnt(10)
	v_mfma_f32_32x32x16_bf16 v[50:65], v[224:227], v[78:81], v[50:65]
	v_mfma_f32_32x32x16_bf16 v[34:49], v[228:231], v[78:81], v[34:49]
	ds_read2_b64 v[224:227], v143 offset0:8 offset1:10
	ds_read2_b64 v[228:231], v143 offset0:12 offset1:14
	s_waitcnt lgkmcnt(10)
	v_mfma_f32_32x32x16_bf16 v[50:65], v[232:235], v[82:85], v[50:65]
	v_mfma_f32_32x32x16_bf16 v[34:49], v[236:239], v[82:85], v[34:49]
	s_waitcnt lgkmcnt(8)
	v_mfma_f32_32x32x16_bf16 v[50:65], v[240:243], v[86:89], v[50:65]
	v_mfma_f32_32x32x16_bf16 v[34:49], v[244:247], v[86:89], v[34:49]
	s_cbranch_scc1 .Lsb_nomask
	v_add_u32_e32 v1, s42, v112
	v_add_u32_e32 v138, 32, v1
	v_cmp_le_i32_e32 vcc, v138, v135
	v_add_u32_e32 v138, 33, v1
	s_nop 6
	v_cndmask_b32_e32 v34, v173, v34, vcc
	v_cmp_lt_i32_e32 vcc, v1, v135
	s_nop 1
	v_cndmask_b32_e32 v51, v173, v51, vcc
	v_cmp_le_i32_e32 vcc, v1, v135
	s_nop 1
	v_cndmask_b32_e32 v50, v173, v50, vcc
	v_cmp_le_i32_e32 vcc, v138, v135
	v_add_u32_e32 v138, 2, v1
	s_nop 0
	v_cndmask_b32_e32 v35, v173, v35, vcc
	v_cmp_le_i32_e32 vcc, v138, v135
	v_add_u32_e32 v138, 34, v1
	s_nop 0
	v_cndmask_b32_e32 v52, v173, v52, vcc
	v_cmp_le_i32_e32 vcc, v138, v135
	v_add_u32_e32 v138, 3, v1
	s_nop 0
	v_cndmask_b32_e32 v36, v173, v36, vcc
	v_cmp_le_i32_e32 vcc, v138, v135
	v_add_u32_e32 v138, 35, v1
	s_nop 0
	v_cndmask_b32_e32 v53, v173, v53, vcc
	v_cmp_le_i32_e32 vcc, v138, v135
	v_add_u32_e32 v138, 8, v1
	s_nop 0
	v_cndmask_b32_e32 v37, v173, v37, vcc
	v_cmp_le_i32_e32 vcc, v138, v135
	v_add_u32_e32 v138, 40, v1
	s_nop 0
	v_cndmask_b32_e32 v54, v173, v54, vcc
	v_cmp_le_i32_e32 vcc, v138, v135
	v_add_u32_e32 v138, 9, v1
	s_nop 0
	v_cndmask_b32_e32 v38, v173, v38, vcc
	v_cmp_le_i32_e32 vcc, v138, v135
	v_add_u32_e32 v138, 41, v1
	s_nop 0
	v_cndmask_b32_e32 v55, v173, v55, vcc
	v_cmp_le_i32_e32 vcc, v138, v135
	v_add_u32_e32 v138, 10, v1
	s_nop 0
	v_cndmask_b32_e32 v39, v173, v39, vcc
	v_cmp_le_i32_e32 vcc, v138, v135
	v_add_u32_e32 v138, 42, v1
	s_nop 0
	v_cndmask_b32_e32 v56, v173, v56, vcc
	v_cmp_le_i32_e32 vcc, v138, v135
	v_add_u32_e32 v138, 11, v1
	s_nop 0
	v_cndmask_b32_e32 v40, v173, v40, vcc
	v_cmp_le_i32_e32 vcc, v138, v135
	v_add_u32_e32 v138, 43, v1
	s_nop 0
	v_cndmask_b32_e32 v57, v173, v57, vcc
	v_cmp_le_i32_e32 vcc, v138, v135
	v_add_u32_e32 v138, 16, v1
	s_nop 0
	v_cndmask_b32_e32 v41, v173, v41, vcc
	v_cmp_le_i32_e32 vcc, v138, v135
	v_add_u32_e32 v138, 48, v1
	s_nop 0
	v_cndmask_b32_e32 v58, v173, v58, vcc
	v_cmp_le_i32_e32 vcc, v138, v135
	v_add_u32_e32 v138, 17, v1
	s_nop 0
	v_cndmask_b32_e32 v42, v173, v42, vcc
	v_cmp_le_i32_e32 vcc, v138, v135
	v_add_u32_e32 v138, 49, v1
	s_nop 0
	v_cndmask_b32_e32 v59, v173, v59, vcc
	v_cmp_le_i32_e32 vcc, v138, v135
	v_add_u32_e32 v138, 18, v1
	s_nop 0
	v_cndmask_b32_e32 v43, v173, v43, vcc
	v_cmp_le_i32_e32 vcc, v138, v135
	v_add_u32_e32 v138, 50, v1
	s_nop 0
	v_cndmask_b32_e32 v60, v173, v60, vcc
	v_cmp_le_i32_e32 vcc, v138, v135
	v_add_u32_e32 v138, 19, v1
	s_nop 0
	v_cndmask_b32_e32 v44, v173, v44, vcc
	v_cmp_le_i32_e32 vcc, v138, v135
	v_add_u32_e32 v138, 51, v1
	s_nop 0
	v_cndmask_b32_e32 v61, v173, v61, vcc
	v_cmp_le_i32_e32 vcc, v138, v135
	v_add_u32_e32 v138, 24, v1
	s_nop 0
	v_cndmask_b32_e32 v45, v173, v45, vcc
	v_cmp_le_i32_e32 vcc, v138, v135
	v_add_u32_e32 v138, 56, v1
	s_nop 0
	v_cndmask_b32_e32 v62, v173, v62, vcc
	v_cmp_le_i32_e32 vcc, v138, v135
	v_add_u32_e32 v138, 25, v1
	s_nop 0
	v_cndmask_b32_e32 v46, v173, v46, vcc
	v_cmp_le_i32_e32 vcc, v138, v135
	v_add_u32_e32 v138, 57, v1
	s_nop 0
	v_cndmask_b32_e32 v63, v173, v63, vcc
	v_cmp_le_i32_e32 vcc, v138, v135
	v_add_u32_e32 v138, 26, v1
	s_nop 0
	v_cndmask_b32_e32 v47, v173, v47, vcc
	v_cmp_le_i32_e32 vcc, v138, v135
	v_add_u32_e32 v138, 58, v1
	s_nop 0
	v_cndmask_b32_e32 v64, v173, v64, vcc
	v_cmp_le_i32_e32 vcc, v138, v135
	v_add_u32_e32 v138, 27, v1
	v_add_u32_e32 v1, 59, v1
	v_cndmask_b32_e32 v48, v173, v48, vcc
	v_cmp_le_i32_e32 vcc, v138, v135
	s_nop 1
	v_cndmask_b32_e32 v65, v173, v65, vcc
	v_cmp_le_i32_e32 vcc, v1, v135
	s_nop 1
	v_cndmask_b32_e32 v49, v173, v49, vcc
.Lsb_nomask:
.Lsb_noqk:
	s_andn2_b64 vcc, exec, s[2:3]
	s_cbranch_vccnz .Lsb_134
.Lsb_st:
	s_xor_b32 s10, s18, 1
	s_mul_i32 s2, s10, 0x3400
	s_add_i32 s11, s80, s2
	v_lshlrev_b32_e32 v248, 1, v106
	v_add3_u32 v248, s11, v125, v248
	s_waitcnt vmcnt(0) lgkmcnt(0)
	ds_write_b128 v248, v[90:93]
	s_and_saveexec_b64 s[2:3], s[6:7]
	v_add3_u32 v248, s11, v127, v128
	ds_write_b128 v248, v[94:97]
	s_or_b64 exec, exec, s[2:3]
	s_mulk_i32 s10, 0x2400
	v_add_u32_e32 v248, s10, v129
	ds_write_b128 v248, v[98:101] offset:26624
.Lsb_134:
	s_add_i32 s42, s42, 64
	s_cmp_eq_u32 s27, s31
	s_waitcnt lgkmcnt(0)
	s_barrier
	s_cbranch_scc1 .Lsb_fin
	s_mov_b32 s10, s31
	s_branch .Lsb_loop
.Lsb_fin:
	s_sub_i32 s11, s42, 64
	s_cmp_gt_i32 s11, s29
	s_cbranch_scc1 .Lsb_fin2

; #define PV_STEP(OACC, mm, ktt, ss, PF) do { OACC = __builtin_amdgcn_mfma_f32_32x32x16_bf16(ldA_perm(vb + (mm) * 32 * 72 + 32 * (ktt) + 16 * (ss)), PF, OACC, 0, 0, 0); } while (0)
; __device__ __forceinline__ void attn_phase(const Ctx& c, const Params& p, int o, int first, int cidx) {
;     ...
;                 const float mnew = fmaxf(mrun, mx);
;                 if (__any(mnew > mrun)) { const float alpha = __builtin_amdgcn_exp2f(mrun - mnew); lrun *= alpha; o0 = o0 * alpha; o1 = o1 * alpha; }
;                 mrun = mnew;
;                 f32x16 e0, e1;
; #pragma unroll
;                 for (int r = 0; r < 16; ++r) { e0[r] = __builtin_amdgcn_exp2f(p0[r] - mnew); e1[r] = __builtin_amdgcn_exp2f(p1[r] - mnew); }
;                 p0 = e0; p1 = e1;
;                 { const f32x16 t = e0 + e1; lrun += ((t[0] + t[1]) + (t[2] + t[3])) + ((t[4] + t[5]) + (t[6] + t[7])) + ((t[8] + t[9]) + (t[10] + t[11])) + ((t[12] + t[13]) + (t[14] + t[15])); }
;                 const bf16x8 pf00 = pkfrag(p0, 0), pf01 = pkfrag(p0, 1), pf10 = pkfrag(p1, 0), pf11 = pkfrag(p1, 1);
;     ...
;                 PV_STEP(o0, 0, 0, 0, pf00); PV_STEP(o0, 0, 0, 1, pf01); PV_STEP(o0, 0, 1, 0, pf10); PV_STEP(o0, 0, 1, 1, pf11);
;                 PV_STEP(o1, 1, 0, 0, pf00); PV_STEP(o1, 1, 0, 1, pf01); PV_STEP(o1, 1, 1, 0, pf10); PV_STEP(o1, 1, 1, 1, pf11);
.Lsb_129b:
	v_sub_f32_e32 v38, v38, v1
	v_exp_f32_e32 v138, v38
	v_sub_f32_e32 v38, v55, v1
	v_exp_f32_e32 v55, v38
	v_sub_f32_e32 v38, v39, v1
	v_sub_f32_e32 v39, v40, v1
	v_sub_f32_e32 v40, v41, v1
	v_sub_f32_e32 v41, v42, v1
	v_sub_f32_e32 v42, v43, v1
	v_exp_f32_e32 v139, v38
	v_sub_f32_e32 v38, v56, v1
	v_exp_f32_e32 v56, v39
	v_sub_f32_e32 v39, v57, v1
	v_exp_f32_e32 v57, v40
	v_sub_f32_e32 v40, v58, v1
	v_exp_f32_e32 v58, v41
	v_sub_f32_e32 v41, v59, v1
	v_exp_f32_e32 v59, v42
	v_sub_f32_e32 v42, v60, v1
	v_exp_f32_e32 v60, v42
	v_sub_f32_e32 v42, v44, v1
	v_exp_f32_e32 v140, v42
	v_sub_f32_e32 v42, v61, v1
	v_exp_f32_e32 v61, v42
	v_sub_f32_e32 v42, v45, v1
	v_exp_f32_e32 v141, v42
	v_sub_f32_e32 v42, v62, v1
	v_exp_f32_e32 v44, v42
	v_sub_f32_e32 v42, v46, v1
	v_exp_f32_e32 v62, v42
	v_sub_f32_e32 v42, v63, v1
	v_sub_f32_e32 v50, v50, v1
	v_sub_f32_e32 v34, v34, v1
	v_sub_f32_e32 v51, v51, v1
	v_sub_f32_e32 v35, v35, v1
	v_sub_f32_e32 v52, v52, v1
	v_sub_f32_e32 v36, v36, v1
	v_sub_f32_e32 v53, v53, v1
	v_sub_f32_e32 v37, v37, v1
	v_exp_f32_e32 v45, v42
	v_sub_f32_e32 v42, v47, v1
	v_exp_f32_e32 v50, v50
	v_exp_f32_e32 v34, v34
	v_exp_f32_e32 v51, v51
	v_exp_f32_e32 v35, v35
	v_exp_f32_e32 v52, v52
	v_exp_f32_e32 v36, v36
	v_exp_f32_e32 v53, v53
	v_exp_f32_e32 v37, v37
	v_sub_f32_e32 v54, v54, v1
	v_exp_f32_e32 v63, v42
	v_sub_f32_e32 v42, v64, v1
	v_exp_f32_e32 v54, v54
	v_exp_f32_e32 v38, v38
	v_exp_f32_e32 v39, v39
	v_exp_f32_e32 v64, v42
	v_sub_f32_e32 v42, v48, v1
	v_exp_f32_e32 v142, v42
	v_sub_f32_e32 v42, v65, v1
	v_exp_f32_e32 v65, v42
	v_sub_f32_e32 v42, v49, v1
	v_exp_f32_e32 v40, v40
	v_exp_f32_e32 v41, v41
	v_exp_f32_e32 v143, v42
	v_pk_add_f32 v[184:185], v[52:53], v[36:37]
	v_pk_add_f32 v[186:187], v[50:51], v[34:35]
	v_pk_add_f32 v[170:171], v[38:39], v[56:57]
	v_pk_add_f32 v[174:175], v[54:55], v[138:139]
	v_pk_mov_b32 v[188:189], v[186:187], v[184:185] op_sel:[1,0]
	v_mov_b32_e32 v187, v185
	v_pk_add_f32 v[184:185], v[188:189], v[186:187]
	v_pk_mov_b32 v[186:187], v[174:175], v[170:171] op_sel:[1,0]
	v_mov_b32_e32 v175, v171
	v_pk_add_f32 v[170:171], v[186:187], v[174:175]
	v_pk_add_f32 v[42:43], v[64:65], v[142:143]
	v_pk_add_f32 v[46:47], v[44:45], v[62:63]
	v_pk_add_f32 v[48:49], v[60:61], v[140:141]
	v_pk_add_f32 v[168:169], v[40:41], v[58:59]
	v_pk_add_f32 v[184:185], v[184:185], v[184:185] op_sel_hi:[0,1]
	v_pk_add_f32 v[170:171], v[170:171], v[170:171] op_sel_hi:[0,1]
	v_add_f32_e32 v169, v168, v169
	v_add_f32_e32 v49, v48, v49
	v_mov_b32_e32 v168, v46
	v_mov_b32_e32 v48, v47
	v_mov_b32_e32 v184, v42
	v_mov_b32_e32 v170, v43
	s_mul_i32 s10, s18, 0x2400
	v_pk_add_f32 v[46:47], v[168:169], v[48:49]
	v_pk_add_f32 v[42:43], v[184:185], v[170:171]
	v_cvt_pk_bf16_f32 v49, v38, v39
	v_pk_add_f32 v[42:43], v[46:47], v[42:43]
	v_cvt_pk_bf16_f32 v38, v34, v35
	v_cvt_pk_bf16_f32 v34, v58, v59
	v_add_u32_e32 v58, s10, v131
	v_add_f32_e32 v42, v42, v43
	v_add_u32_e32 v59, 0x6800, v58
	v_add_f32_e32 v136, v42, v136
	v_cvt_pk_bf16_f32 v46, v50, v51
	v_cvt_pk_bf16_f32 v47, v52, v53
	v_cvt_pk_bf16_f32 v48, v54, v55
	v_cvt_pk_bf16_f32 v42, v40, v41
	v_cvt_pk_bf16_f32 v41, v56, v57
	s_waitcnt lgkmcnt(0)
	v_mfma_f32_32x32x16_bf16 v[18:33], v[200:203], v[46:49], v[18:33]
	v_cvt_pk_bf16_f32 v43, v60, v61
	v_cvt_pk_bf16_f32 v44, v44, v45
	v_cvt_pk_bf16_f32 v45, v64, v65
	v_cvt_pk_bf16_f32 v39, v36, v37
	v_cvt_pk_bf16_f32 v40, v138, v139
	v_cvt_pk_bf16_f32 v35, v140, v141
	v_cvt_pk_bf16_f32 v36, v62, v63
	v_cvt_pk_bf16_f32 v37, v142, v143
	v_mfma_f32_32x32x16_bf16 v[2:17], v[216:219], v[46:49], v[2:17]
	v_mfma_f32_32x32x16_bf16 v[18:33], v[204:207], v[42:45], v[18:33]
	v_mfma_f32_32x32x16_bf16 v[2:17], v[220:223], v[42:45], v[2:17]
	v_mfma_f32_32x32x16_bf16 v[18:33], v[208:211], v[38:41], v[18:33]
	v_mfma_f32_32x32x16_bf16 v[2:17], v[224:227], v[38:41], v[2:17]
	v_mfma_f32_32x32x16_bf16 v[18:33], v[212:215], v[34:37], v[18:33]
	v_mfma_f32_32x32x16_bf16 v[2:17], v[228:231], v[34:37], v[2:17]
.Lsb_fin2:
	s_branch .LBB0_110
.LBB0_136:
	s_mov_b64 s[2:3], 0

; __device__ __forceinline__ void gdn_scan(const Ctx& c, const Params& p, int e) {
;     ...
;         if (producer) {
;             int pt_ = ptid; asm volatile("" : "+v"(pt_));
;             u32x4 tq[4], tk[4], tw[4], tu[4], tqk[2];
;             const int prow = pt_ >> 4, pc8 = (pt_ & 15) * 8;
;             const int qrow = pt_ >> 3, qc8 = (pt_ & 7) * 8;
;             GDN_LOAD_TILES(0); GDN_STORE_TILES();
.LBB0_530:
	s_and_b64 vcc, exec, s[2:3]
	s_cbranch_vccz .LBB0_521
	s_mul_hi_i32 s2, s20, 0x2aaaaaab
	s_lshr_b32 s3, s2, 31
	s_add_i32 s2, s2, s3
	s_mul_i32 s3, s2, 6
	s_sub_i32 s3, s20, s3
	s_waitcnt vmcnt(0)
	v_mov_b32_e32 v97, v165
	s_lshl_b32 s4, s2, 13
	v_ashrrev_i32_e32 v64, 4, v97
	v_lshlrev_b32_e32 v1, 3, v97
	s_lshl_b32 s2, s3, 7
	s_waitcnt lgkmcnt(0)
	v_and_b32_e32 v12, 0x78, v1
	s_ashr_i32 s5, s4, 31
	v_ashrrev_i32_e32 v65, 31, v64
	s_ashr_i32 s3, s2, 31
	v_lshl_add_u64 v[2:3], v[64:65], 0, s[4:5]
	v_or_b32_e32 v102, s2, v12
	v_mov_b32_e32 v103, s3
	s_movk_i32 s35, 0x300
	v_and_b32_e32 v66, 56, v1
	v_mad_u64_u32 v[6:7], s[20:21], v2, s35, v[102:103]
	v_add_u32_e32 v1, 0x100, v97
	v_mad_i32_i24 v7, v3, s35, v7
	v_mov_b64_e32 v[10:11], s[16:17]
	v_ashrrev_i32_e32 v106, 4, v1
	v_mad_u64_u32 v[4:5], s[20:21], v2, s69, v[10:11]
	v_lshlrev_b64 v[6:7], 1, v[6:7]
	v_ashrrev_i32_e32 v107, 31, v106
	v_mad_i32_i24 v5, v3, s69, v5
	s_lshl_b64 s[20:21], s[2:3], 1
	v_lshlrev_b32_e32 v114, 4, v97
	v_lshl_add_u64 v[68:69], s[8:9], 0, v[6:7]
	v_lshl_add_u64 v[78:79], s[6:7], 0, v[6:7]
	v_lshl_add_u64 v[6:7], v[106:107], 0, s[4:5]
	v_lshl_add_u64 v[8:9], v[4:5], 0, s[20:21]
	v_lshlrev_b32_e32 v104, 1, v12
	v_mov_b32_e32 v105, v0
	v_and_b32_e32 v4, 0x80, v114
	v_mov_b32_e32 v5, v0
	v_mad_u64_u32 v[32:33], s[2:3], v6, s69, v[10:11]
	v_lshl_add_u64 v[14:15], v[8:9], 0, v[104:105]
	v_lshl_add_u64 v[12:13], v[8:9], 0, v[4:5]
	v_lshlrev_b32_e32 v8, 1, v66
	v_mov_b32_e32 v9, v0
	v_mad_i32_i24 v33, v7, s69, v33
	v_lshl_add_u64 v[12:13], v[12:13], 0, v[8:9]
	v_lshl_add_u64 v[32:33], v[32:33], 0, s[20:21]
	global_load_dwordx4 v[16:19], v[14:15], off offset:1536
	global_load_dwordx4 v[20:23], v[12:13], off offset:3072
	v_add_co_u32_e32 v12, vcc, s47, v14
	v_lshl_add_u64 v[32:33], v[32:33], 0, v[4:5]
	s_nop 0
	v_addc_co_u32_e32 v13, vcc, 0, v15, vcc
	v_lshl_add_u64 v[36:37], v[32:33], 0, v[8:9]
	s_movk_i32 s0, 0x6000
	global_load_dwordx4 v[24:27], v[68:69], off
	global_load_dwordx4 v[28:31], v[78:79], off
	global_load_dwordx4 v[32:35], v[12:13], off offset:2048
	s_nop 0
	global_load_dwordx4 v[36:39], v[36:37], off offset:3072
	v_add_co_u32_e32 v12, vcc, s0, v68
	s_mov_b32 s39, 0x3c000
	s_nop 0
	v_addc_co_u32_e32 v13, vcc, 0, v69, vcc
	v_add_co_u32_e32 v44, vcc, s0, v78
	v_add_u32_e32 v94, 0x200, v97
	s_nop 0
	v_addc_co_u32_e32 v45, vcc, 0, v79, vcc
	v_add_co_u32_e32 v48, vcc, s39, v14
	v_add_u32_e32 v95, 0x300, v97
	s_nop 0
	v_addc_co_u32_e32 v49, vcc, 0, v15, vcc
	v_add_co_u32_e32 v56, vcc, s62, v68
	v_ashrrev_i32_e32 v108, 4, v94
	s_nop 0
	v_addc_co_u32_e32 v57, vcc, 0, v69, vcc
	v_add_co_u32_e32 v60, vcc, s62, v78
	s_mov_b32 s42, 0x5a000
	s_nop 0
	v_addc_co_u32_e32 v61, vcc, 0, v79, vcc
	v_ashrrev_i32_e32 v110, 4, v95
	v_ashrrev_i32_e32 v109, 31, v108
	v_add_co_u32_e32 v70, vcc, s42, v14
	v_ashrrev_i32_e32 v111, 31, v110
	global_load_dwordx4 v[40:43], v[12:13], off
	s_nop 0
	global_load_dwordx4 v[44:47], v[44:45], off
	v_lshl_add_u64 v[12:13], v[108:109], 0, s[4:5]
	v_addc_co_u32_e32 v71, vcc, 0, v15, vcc
	v_lshl_add_u64 v[14:15], v[110:111], 0, s[4:5]
	v_mad_u64_u32 v[50:51], s[2:3], v12, s69, v[10:11]
	v_mad_u64_u32 v[72:73], s[2:3], v14, s69, v[10:11]
	v_mad_i32_i24 v51, v13, s69, v51
	v_mad_i32_i24 v73, v15, s69, v73
	v_add_co_u32_e32 v68, vcc, s63, v68
	v_lshl_add_u64 v[50:51], v[50:51], 0, s[20:21]
	v_lshl_add_u64 v[72:73], v[72:73], 0, s[20:21]
	v_addc_co_u32_e32 v69, vcc, 0, v69, vcc
	v_lshl_add_u64 v[50:51], v[50:51], 0, v[4:5]
	v_lshl_add_u64 v[72:73], v[72:73], 0, v[4:5]
	v_add_co_u32_e32 v82, vcc, s63, v78
	v_lshl_add_u64 v[52:53], v[50:51], 0, v[8:9]
	v_lshl_add_u64 v[74:75], v[72:73], 0, v[8:9]
	v_addc_co_u32_e32 v83, vcc, 0, v79, vcc
	global_load_dwordx4 v[48:51], v[48:49], off offset:2560
	s_nop 0
	global_load_dwordx4 v[52:55], v[52:53], off offset:3072
	s_nop 0
	global_load_dwordx4 v[56:59], v[56:57], off
	s_nop 0
	global_load_dwordx4 v[60:63], v[60:61], off
	s_nop 0
	global_load_dwordx4 v[70:73], v[70:71], off offset:3072
	s_nop 0
	global_load_dwordx4 v[74:77], v[74:75], off offset:3072
	s_nop 0
	global_load_dwordx4 v[78:81], v[68:69], off
	s_nop 0
	global_load_dwordx4 v[82:85], v[82:83], off
	v_ashrrev_i32_e32 v68, 3, v97
	v_ashrrev_i32_e32 v69, 31, v68
	v_lshl_add_u64 v[112:113], v[68:69], 0, s[4:5]
	v_mad_u64_u32 v[86:87], s[2:3], v112, s69, v[10:11]
	v_mad_i32_i24 v87, v113, s69, v87
	v_lshl_add_u64 v[86:87], v[86:87], 0, s[20:21]
	v_lshl_add_u64 v[86:87], v[86:87], 0, v[8:9]
	s_movk_i32 s5, 0x1000
	v_add_co_u32_e32 v88, vcc, s5, v86
	s_mov_b32 s44, 0x3d000
	s_nop 0
	v_addc_co_u32_e32 v89, vcc, 0, v87, vcc
	v_add_co_u32_e32 v90, vcc, s44, v86
	v_mul_lo_u32 v67, v64, s36
	s_nop 0
	v_addc_co_u32_e32 v91, vcc, 0, v87, vcc
	global_load_dwordx4 v[86:89], v[88:89], off offset:512
	s_nop 0
	global_load_dwordx4 v[98:101], v[90:91], off offset:1536
	v_add3_u32 v91, s80, v104, v67
	s_waitcnt vmcnt(0) lgkmcnt(0)
; #define LDS_BARRIER() do { asm volatile("s_waitcnt lgkmcnt(0)" ::: "memory"); __builtin_amdgcn_s_barrier(); asm volatile("" ::: "memory"); } while (0)
; #define GDN_STORE_O(nn) do { const LAS bf16_t* ob_ = OTb + ((nn) & 1) * 4608; _Pragma("unroll") for (int k_ = 0; k_ < 2; ++k_) { const int vi_ = pt_ + 256 * k_, row_ = vi_ >> 3, c8_ = (vi_ & 7) * 8; \
;             *(u32x4*)(Y + (size_t)(b * T_ + 64 * (nn) + row_) * D_ + 256 + h * 128 + 64 * dvh + c8_) = *(const LAS u32x4*)(ob_ + row_ * 72 + c8_); } } while (0)
; __device__ __forceinline__ void gdn_scan(const Ctx& c, const Params& p, int e) {
;     ...
;             GDN_LOAD_TILES(0); GDN_STORE_TILES();
;             for (int n = 0; n < 128; ++n) {
;                 LDS_BARRIER();
;                 if (n + 1 < 128) GDN_LOAD_TILES(n + 1);
;                 if (n >= 1) GDN_STORE_O(n - 1);
;                 LDS_BARRIER();
;                 if (n + 1 < 128) GDN_STORE_TILES();
	ds_write_b128 v91, v[16:19]
	ds_write_b128 v91, v[24:27] offset:17408
	ds_write_b128 v91, v[28:31] offset:34816
	s_movk_i32 s2, 0x90
	v_lshrrev_b32_e32 v116, 3, v94
	v_add_u32_e32 v96, s80, v8
	v_mul_lo_u32 v116, v116, s2
	v_ashrrev_i32_e32 v1, 3, v1
	v_add_u32_e32 v94, v96, v116
	v_lshrrev_b32_e32 v116, 3, v95
	v_mul_lo_u32 v90, v68, s2
	v_mul_lo_u32 v67, v1, s2
	v_mul_lo_u32 v116, v116, s2
	s_or_b32 s2, s4, 64
	v_add_u32_e32 v95, v96, v116
	v_add_u32_e32 v116, s24, v8
	s_ashr_i32 s3, s2, 31
	v_add_u32_e32 v92, v96, v90
	v_add_u32_e32 v93, v96, v67
	v_add_u32_e32 v96, v116, v90
	v_lshl_add_u64 v[116:117], v[64:65], 0, s[2:3]
	v_mad_u64_u32 v[118:119], s[40:41], v116, s69, v[10:11]
	v_mad_u64_u32 v[120:121], s[40:41], v116, s35, v[102:103]
	v_mad_i32_i24 v119, v117, s69, v119
	v_mad_i32_i24 v121, v117, s35, v121
	v_lshl_add_u64 v[116:117], v[118:119], 0, s[20:21]
	v_lshl_add_u64 v[64:65], v[116:117], 0, v[104:105]
	ds_write_b128 v92, v[20:23] offset:52224
	ds_write_b128 v91, v[32:35] offset:4352
	ds_write_b128 v91, v[40:43] offset:21760
	ds_write_b128 v91, v[44:47] offset:39168
	v_lshlrev_b64 v[120:121], 1, v[120:121]
	v_add_co_u32_e32 v132, vcc, s47, v64
	ds_write_b128 v93, v[36:39] offset:52224
	ds_write_b128 v91, v[48:51] offset:8704
	ds_write_b128 v91, v[56:59] offset:26112
	ds_write_b128 v91, v[60:63] offset:43520
	ds_write_b128 v94, v[52:55] offset:52224
	ds_write_b128 v91, v[70:73] offset:13056
	ds_write_b128 v91, v[78:81] offset:30464
	ds_write_b128 v91, v[82:85] offset:47872
	v_lshl_add_u64 v[224:225], s[8:9], 0, v[120:121]
	v_addc_co_u32_e32 v133, vcc, 0, v65, vcc
	v_add_co_u32_e32 v136, vcc, s0, v224
	v_lshl_add_u64 v[226:227], s[6:7], 0, v[120:121]
	s_nop 0
	v_addc_co_u32_e32 v137, vcc, 0, v225, vcc
	v_add_co_u32_e32 v140, vcc, s0, v226
	v_lshl_add_u64 v[134:135], v[106:107], 0, s[2:3]
	s_nop 0
	v_addc_co_u32_e32 v141, vcc, 0, v227, vcc
	v_add_co_u32_e32 v204, vcc, s39, v64
	v_lshl_add_u64 v[206:207], v[108:109], 0, s[2:3]
	s_nop 0
	v_addc_co_u32_e32 v205, vcc, 0, v65, vcc
	v_add_co_u32_e32 v208, vcc, s62, v224
	v_lshl_add_u64 v[220:221], v[110:111], 0, s[2:3]
	v_mad_u64_u32 v[200:201], s[40:41], v134, s69, v[10:11]
	v_mad_u64_u32 v[216:217], s[40:41], v206, s69, v[10:11]
	v_addc_co_u32_e32 v209, vcc, 0, v225, vcc
	v_mad_u64_u32 v[222:223], s[40:41], v220, s69, v[10:11]
	ds_write_b128 v95, v[74:77] offset:52224
	ds_write_b128 v96, v[86:89]
	ds_write_b128 v96, v[98:101] offset:4608
	v_lshl_add_u64 v[116:117], v[116:117], 0, v[4:5]
	v_mad_i32_i24 v201, v135, s69, v201
	v_mad_i32_i24 v217, v207, s69, v217
	v_add_co_u32_e32 v212, vcc, s62, v226
	v_mad_i32_i24 v223, v221, s69, v223
	v_lshl_add_u64 v[128:129], v[116:117], 0, v[8:9]
	v_lshl_add_u64 v[134:135], v[200:201], 0, s[20:21]
	v_lshl_add_u64 v[206:207], v[216:217], 0, s[20:21]
	v_addc_co_u32_e32 v213, vcc, 0, v227, vcc
	v_lshl_add_u64 v[220:221], v[222:223], 0, s[20:21]
	global_load_dwordx4 v[116:119], v[64:65], off offset:1536
	s_nop 0
	global_load_dwordx4 v[128:131], v[128:129], off offset:3072
	v_lshl_add_u64 v[134:135], v[134:135], 0, v[4:5]
	v_lshl_add_u64 v[206:207], v[206:207], 0, v[4:5]
	v_add_co_u32_e32 v64, vcc, s42, v64
	v_lshl_add_u64 v[220:221], v[220:221], 0, v[4:5]
	v_lshl_add_u64 v[200:201], v[134:135], 0, v[8:9]
	v_lshl_add_u64 v[216:217], v[206:207], 0, v[8:9]
	v_addc_co_u32_e32 v65, vcc, 0, v65, vcc
	v_lshl_add_u64 v[232:233], v[220:221], 0, v[8:9]
	global_load_dwordx4 v[120:123], v[224:225], off
	global_load_dwordx4 v[124:127], v[226:227], off
	s_nop 0
	global_load_dwordx4 v[132:135], v[132:133], off offset:2048
	s_nop 0
	global_load_dwordx4 v[200:203], v[200:201], off offset:3072
	s_nop 0
	global_load_dwordx4 v[136:139], v[136:137], off
	s_nop 0
	global_load_dwordx4 v[140:143], v[140:141], off
	s_nop 0
	global_load_dwordx4 v[204:207], v[204:205], off offset:2560
	s_nop 0
	global_load_dwordx4 v[216:219], v[216:217], off offset:3072
	s_nop 0
	global_load_dwordx4 v[208:211], v[208:209], off
	s_nop 0
	global_load_dwordx4 v[212:215], v[212:213], off
	s_nop 0
	global_load_dwordx4 v[220:223], v[64:65], off offset:3072
	s_nop 0
	global_load_dwordx4 v[232:235], v[232:233], off offset:3072
	v_add_co_u32_e32 v64, vcc, s63, v224
	s_nop 1
	v_addc_co_u32_e32 v65, vcc, 0, v225, vcc
	v_add_co_u32_e32 v228, vcc, s63, v226
	s_nop 1
	v_addc_co_u32_e32 v229, vcc, 0, v227, vcc
	global_load_dwordx4 v[224:227], v[64:65], off
	s_nop 0
	global_load_dwordx4 v[228:231], v[228:229], off
	v_lshl_add_u64 v[64:65], v[68:69], 0, s[2:3]
	v_mad_u64_u32 v[10:11], s[2:3], v64, s69, v[10:11]
	v_mad_i32_i24 v11, v65, s69, v11
	v_lshl_add_u64 v[10:11], v[10:11], 0, s[20:21]
	v_lshl_add_u64 v[10:11], v[10:11], 0, v[8:9]
	v_add_co_u32_e32 v64, vcc, s5, v10
	s_add_u32 s3, s74, s20
	s_nop 0
	v_addc_co_u32_e32 v65, vcc, 0, v11, vcc
	v_add_co_u32_e32 v10, vcc, s44, v10
	s_addc_u32 s5, s75, s21
	s_nop 0
	v_addc_co_u32_e32 v11, vcc, 0, v11, vcc
	global_load_dwordx4 v[236:239], v[64:65], off offset:512
	global_load_dwordx4 v[240:243], v[10:11], off offset:1536
	s_lshl_b32 s35, s34, 1
	s_add_u32 s40, s3, s35
	s_addc_u32 s41, s5, 0
	v_add_u32_e32 v69, s25, v8
	v_lshl_add_u64 v[70:71], s[40:41], 0, v[8:9]
	v_and_b32_e32 v8, 7, v97
	v_lshlrev_b32_e32 v8, 4, v8
	v_mad_u64_u32 v[10:11], s[40:41], v112, s69, v[8:9]
	v_mad_i32_i24 v11, v113, s69, v11
	v_lshl_add_u64 v[76:77], s[22:23], 0, v[10:11]
	v_mad_u64_u32 v[10:11], s[40:41], v14, s69, v[4:5]
	v_mad_i32_i24 v11, v15, s69, v11
	v_lshl_add_u64 v[10:11], v[10:11], 0, v[8:9]
	v_lshl_add_u64 v[78:79], s[18:19], 0, v[10:11]
	v_mad_u64_u32 v[10:11], s[40:41], v12, s69, v[4:5]
	v_mad_i32_i24 v11, v13, s69, v11
	v_lshl_add_u64 v[10:11], v[10:11], 0, v[8:9]
	v_lshl_add_u64 v[80:81], s[18:19], 0, v[10:11]
	v_mad_u64_u32 v[10:11], s[40:41], v6, s69, v[4:5]
	v_mad_i32_i24 v11, v7, s69, v11
	v_mad_u64_u32 v[4:5], s[40:41], v2, s69, v[4:5]
	v_lshl_add_u64 v[6:7], v[10:11], 0, v[8:9]
	v_mad_i32_i24 v5, v3, s69, v5
	v_lshl_add_u64 v[82:83], s[18:19], 0, v[6:7]
	v_and_b32_e32 v6, 0xf0, v114
	v_mov_b32_e32 v7, v0
	v_lshl_add_u64 v[4:5], v[4:5], 0, v[8:9]
	v_mad_u64_u32 v[10:11], s[40:41], v2, s69, v[6:7]
	v_lshl_add_u64 v[86:87], s[18:19], 0, v[4:5]
	v_mad_u64_u32 v[4:5], s[40:41], v2, s50, 0
	v_mad_i32_i24 v11, v3, s69, v11
	v_mad_i32_i24 v3, v3, s50, v5
	v_or_b32_e32 v2, v4, v6
	s_mov_b32 s2, 0
	v_add_u32_e32 v72, s4, v1
	v_add_u32_e32 v74, s4, v68
	v_lshl_add_u64 v[84:85], s[22:23], 0, v[10:11]
	v_lshl_add_u64 v[88:89], s[22:23], 0, v[2:3]
	s_mov_b32 s2, -1
	v_subrev_u32_e32 v72, 64, v72
	v_subrev_u32_e32 v74, 64, v74
; #define LDS_BARRIER() do { asm volatile("s_waitcnt lgkmcnt(0)" ::: "memory"); __builtin_amdgcn_s_barrier(); asm volatile("" ::: "memory"); } while (0)
; #define GDN_STORE_O(nn) do { const LAS bf16_t* ob_ = OTb + ((nn) & 1) * 4608; _Pragma("unroll") for (int k_ = 0; k_ < 2; ++k_) { const int vi_ = pt_ + 256 * k_, row_ = vi_ >> 3, c8_ = (vi_ & 7) * 8; \
;             *(u32x4*)(Y + (size_t)(b * T_ + 64 * (nn) + row_) * D_ + 256 + h * 128 + 64 * dvh + c8_) = *(const LAS u32x4*)(ob_ + row_ * 72 + c8_); } } while (0)
; __device__ __forceinline__ void gdn_scan(const Ctx& c, const Params& p, int e) {
;     ...
;             for (int n = 0; n < 128; ++n) {
;                 LDS_BARRIER();
;                 if (n + 1 < 128) GDN_LOAD_TILES(n + 1);
;                 if (n >= 1) GDN_STORE_O(n - 1);
;                 LDS_BARRIER();
;                 if (n + 1 < 128) GDN_STORE_TILES();
.Lgp_even:
	s_waitcnt lgkmcnt(0)
	s_barrier
	s_cmp_lt_i32 s2, 0
	s_cbranch_scc1 .Lgp_e_nost
	s_bitcmp1_b32 s2, 0
	s_cselect_b32 s3, 0x2400, 0
	v_add_u32_e32 v73, s3, v69
	v_add_u32_e32 v75, v73, v90
	ds_read_b128 v[106:109], v75
	v_ashrrev_i32_e32 v75, 31, v74
	v_lshlrev_b64 v[110:111], 11, v[74:75]
	v_lshl_add_u64 v[110:111], v[70:71], 0, v[110:111]
	v_add_u32_e32 v73, v73, v67
	s_waitcnt lgkmcnt(0)
	global_store_dwordx4 v[110:111], v[106:109], off offset:512
	ds_read_b128 v[106:109], v73
	v_ashrrev_i32_e32 v73, 31, v72
	v_lshlrev_b64 v[110:111], 11, v[72:73]
	v_lshl_add_u64 v[110:111], v[70:71], 0, v[110:111]
	s_waitcnt lgkmcnt(0)
	global_store_dwordx4 v[110:111], v[106:109], off offset:512
.Lgp_e_nost:
	s_cmpk_eq_i32 s2, 0x7d
	s_cbranch_scc1 .Lgp_e_nold
	v_lshl_add_u64 v[50:51], v[84:85], 0, s[20:21]
	v_add_co_u32_e32 v2, vcc, 0x81f1000, v50
	v_lshl_add_u64 v[62:63], v[88:89], 0, s[20:21]
	s_nop 0
	v_addc_co_u32_e32 v3, vcc, 0, v51, vcc
	v_add_co_u32_e32 v10, vcc, 0x1a230000, v62
	s_nop 0
	v_addc_co_u32_e32 v11, vcc, 0, v63, vcc
	v_add_co_u32_e32 v14, vcc, 0x17230000, v62
	global_load_dwordx4 v[2:5], v[2:3], off offset:1536
	s_nop 0
	v_addc_co_u32_e32 v15, vcc, 0, v63, vcc
	v_add_co_u32_e32 v18, vcc, 0x820f000, v50
	global_load_dwordx4 v[10:13], v[10:11], off
	s_nop 0
	v_addc_co_u32_e32 v19, vcc, 0, v51, vcc
	v_add_co_u32_e32 v26, vcc, 0x1a236000, v62
	v_lshl_add_u64 v[6:7], v[86:87], 0, s[20:21]
	s_nop 0
	v_addc_co_u32_e32 v27, vcc, 0, v63, vcc
	v_add_co_u32_e32 v30, vcc, 0x17236000, v62
	global_load_dwordx4 v[14:17], v[14:15], off
	s_nop 0
	v_addc_co_u32_e32 v31, vcc, 0, v63, vcc
	v_add_co_u32_e32 v34, vcc, 0x822d000, v50
	global_load_dwordx4 v[6:9], v[6:7], off
	s_nop 0
	v_addc_co_u32_e32 v35, vcc, 0, v51, vcc
	v_add_co_u32_e32 v42, vcc, 0x1a23c000, v62
	global_load_dwordx4 v[18:21], v[18:19], off offset:2048
	s_nop 0
	v_addc_co_u32_e32 v43, vcc, 0, v63, vcc
	global_load_dwordx4 v[26:29], v[26:27], off
	v_add_co_u32_e32 v46, vcc, 0x1723c000, v62
	v_lshl_add_u64 v[22:23], v[82:83], 0, s[20:21]
	global_load_dwordx4 v[30:33], v[30:31], off
	v_addc_co_u32_e32 v47, vcc, 0, v63, vcc
	global_load_dwordx4 v[22:25], v[22:23], off
	v_add_co_u32_e32 v50, vcc, 0x824b000, v50
	global_load_dwordx4 v[34:37], v[34:35], off offset:2560
	s_nop 0
	v_addc_co_u32_e32 v51, vcc, 0, v51, vcc
	global_load_dwordx4 v[42:45], v[42:43], off
	v_add_co_u32_e32 v58, vcc, 0x1a242000, v62
	v_lshl_add_u64 v[38:39], v[80:81], 0, s[20:21]
	global_load_dwordx4 v[46:49], v[46:47], off
	v_addc_co_u32_e32 v59, vcc, 0, v63, vcc
	global_load_dwordx4 v[38:41], v[38:39], off
	v_add_co_u32_e32 v62, vcc, 0x17242000, v62
	global_load_dwordx4 v[50:53], v[50:51], off offset:3072
	s_nop 0
	v_addc_co_u32_e32 v63, vcc, 0, v63, vcc
	v_lshl_add_u64 v[102:103], v[76:77], 0, s[20:21]
	global_load_dwordx4 v[58:61], v[58:59], off
	v_add_co_u32_e32 v98, vcc, 0x81f2000, v102
	v_lshl_add_u64 v[54:55], v[78:79], 0, s[20:21]
	global_load_dwordx4 v[62:65], v[62:63], off
	v_addc_co_u32_e32 v99, vcc, 0, v103, vcc
	global_load_dwordx4 v[54:57], v[54:55], off
	v_add_co_u32_e32 v102, vcc, 0x822e000, v102
	global_load_dwordx4 v[98:101], v[98:99], off offset:512
	s_nop 0
	v_addc_co_u32_e32 v103, vcc, 0, v103, vcc
	global_load_dwordx4 v[102:105], v[102:103], off offset:1536
.Lgp_e_nold:
	s_add_i32 s2, s2, 1
	s_waitcnt lgkmcnt(0)
	s_barrier
	s_mov_b64 s[40:41], 0x18000
	v_add_u32_e32 v72, 64, v72
	v_add_u32_e32 v74, 64, v74
	v_lshl_add_u64 v[76:77], v[76:77], 0, s[76:77]
	v_lshl_add_u64 v[78:79], v[78:79], 0, s[76:77]
	v_lshl_add_u64 v[80:81], v[80:81], 0, s[76:77]
	v_lshl_add_u64 v[82:83], v[82:83], 0, s[76:77]
	v_lshl_add_u64 v[84:85], v[84:85], 0, s[76:77]
	v_lshl_add_u64 v[86:87], v[86:87], 0, s[76:77]
	v_lshl_add_u64 v[88:89], v[88:89], 0, s[40:41]
	s_cmpk_eq_i32 s2, 0x7e
	s_cbranch_scc1 .Lgp_e_w0
	s_waitcnt vmcnt(18)
	s_branch .Lgp_e_wr

; #define LDS_BARRIER() do { asm volatile("s_waitcnt lgkmcnt(0)" ::: "memory"); __builtin_amdgcn_s_barrier(); asm volatile("" ::: "memory"); } while (0)
; #define GDN_STORE_O(nn) do { const LAS bf16_t* ob_ = OTb + ((nn) & 1) * 4608; _Pragma("unroll") for (int k_ = 0; k_ < 2; ++k_) { const int vi_ = pt_ + 256 * k_, row_ = vi_ >> 3, c8_ = (vi_ & 7) * 8; \
;             *(u32x4*)(Y + (size_t)(b * T_ + 64 * (nn) + row_) * D_ + 256 + h * 128 + 64 * dvh + c8_) = *(const LAS u32x4*)(ob_ + row_ * 72 + c8_); } } while (0)
; __device__ __forceinline__ void gdn_scan(const Ctx& c, const Params& p, int e) {
;     ...
;             for (int n = 0; n < 128; ++n) {
;                 LDS_BARRIER();
;                 if (n + 1 < 128) GDN_LOAD_TILES(n + 1);
;                 if (n >= 1) GDN_STORE_O(n - 1);
;                 LDS_BARRIER();
;                 if (n + 1 < 128) GDN_STORE_TILES();
.Lgp_e_wr:
	ds_write_b128 v91, v[116:119]
	ds_write_b128 v91, v[120:123] offset:17408
	ds_write_b128 v91, v[124:127] offset:34816
	ds_write_b128 v92, v[128:131] offset:52224
	ds_write_b128 v91, v[132:135] offset:4352
	ds_write_b128 v91, v[136:139] offset:21760
	ds_write_b128 v91, v[140:143] offset:39168
	ds_write_b128 v93, v[200:203] offset:52224
	ds_write_b128 v91, v[204:207] offset:8704
	ds_write_b128 v91, v[208:211] offset:26112
	ds_write_b128 v91, v[212:215] offset:43520
	ds_write_b128 v94, v[216:219] offset:52224
	ds_write_b128 v91, v[220:223] offset:13056
	ds_write_b128 v91, v[224:227] offset:30464
	ds_write_b128 v91, v[228:231] offset:47872
	ds_write_b128 v95, v[232:235] offset:52224
	ds_write_b128 v96, v[236:239]
	ds_write_b128 v96, v[240:243] offset:4608
	s_cmpk_eq_i32 s2, 0x7e
	s_cbranch_scc1 .Lgp_done
	s_waitcnt lgkmcnt(0)
	s_barrier
	s_bitcmp1_b32 s2, 0
	s_cselect_b32 s3, 0x2400, 0
	v_add_u32_e32 v73, s3, v69
	v_add_u32_e32 v75, v73, v90
	ds_read_b128 v[106:109], v75
	v_ashrrev_i32_e32 v75, 31, v74
	v_lshlrev_b64 v[110:111], 11, v[74:75]
	v_lshl_add_u64 v[110:111], v[70:71], 0, v[110:111]
	v_add_u32_e32 v73, v73, v67
	s_waitcnt lgkmcnt(0)
	global_store_dwordx4 v[110:111], v[106:109], off offset:512
	ds_read_b128 v[106:109], v73
	v_ashrrev_i32_e32 v73, 31, v72
	v_lshlrev_b64 v[110:111], 11, v[72:73]
	v_lshl_add_u64 v[110:111], v[70:71], 0, v[110:111]
	s_waitcnt lgkmcnt(0)
	global_store_dwordx4 v[110:111], v[106:109], off offset:512
	v_lshl_add_u64 v[220:221], v[84:85], 0, s[20:21]
	v_add_co_u32_e32 v116, vcc, 0x81f1000, v220
	v_lshl_add_u64 v[228:229], v[88:89], 0, s[20:21]
	s_nop 0
	v_addc_co_u32_e32 v117, vcc, 0, v221, vcc
	v_add_co_u32_e32 v120, vcc, 0x1a230000, v228
	s_nop 0
	v_addc_co_u32_e32 v121, vcc, 0, v229, vcc
	v_add_co_u32_e32 v124, vcc, 0x17230000, v228
	global_load_dwordx4 v[116:119], v[116:117], off offset:1536
	s_nop 0
	v_addc_co_u32_e32 v125, vcc, 0, v229, vcc
	v_add_co_u32_e32 v132, vcc, 0x820f000, v220
	global_load_dwordx4 v[120:123], v[120:121], off
	s_nop 0
	v_addc_co_u32_e32 v133, vcc, 0, v221, vcc
	v_add_co_u32_e32 v136, vcc, 0x1a236000, v228
	v_lshl_add_u64 v[128:129], v[86:87], 0, s[20:21]
	s_nop 0
	v_addc_co_u32_e32 v137, vcc, 0, v229, vcc
	v_add_co_u32_e32 v140, vcc, 0x17236000, v228
	global_load_dwordx4 v[124:127], v[124:125], off
	s_nop 0
	v_addc_co_u32_e32 v141, vcc, 0, v229, vcc
	v_add_co_u32_e32 v204, vcc, 0x822d000, v220
	global_load_dwordx4 v[128:131], v[128:129], off
	s_nop 0
	v_addc_co_u32_e32 v205, vcc, 0, v221, vcc
	v_add_co_u32_e32 v208, vcc, 0x1a23c000, v228
	global_load_dwordx4 v[132:135], v[132:133], off offset:2048
	s_nop 0
	v_addc_co_u32_e32 v209, vcc, 0, v229, vcc
	global_load_dwordx4 v[136:139], v[136:137], off
	v_add_co_u32_e32 v212, vcc, 0x1723c000, v228
	v_lshl_add_u64 v[200:201], v[82:83], 0, s[20:21]
	global_load_dwordx4 v[140:143], v[140:141], off
	v_addc_co_u32_e32 v213, vcc, 0, v229, vcc
	global_load_dwordx4 v[200:203], v[200:201], off
	v_add_co_u32_e32 v220, vcc, 0x824b000, v220
	global_load_dwordx4 v[204:207], v[204:205], off offset:2560
	s_nop 0
	v_addc_co_u32_e32 v221, vcc, 0, v221, vcc
	global_load_dwordx4 v[208:211], v[208:209], off
	v_add_co_u32_e32 v224, vcc, 0x1a242000, v228
	v_lshl_add_u64 v[216:217], v[80:81], 0, s[20:21]
	global_load_dwordx4 v[212:215], v[212:213], off
	v_addc_co_u32_e32 v225, vcc, 0, v229, vcc
	global_load_dwordx4 v[216:219], v[216:217], off
	v_add_co_u32_e32 v228, vcc, 0x17242000, v228
	global_load_dwordx4 v[220:223], v[220:221], off offset:3072
	s_nop 0
	v_addc_co_u32_e32 v229, vcc, 0, v229, vcc
	v_lshl_add_u64 v[240:241], v[76:77], 0, s[20:21]
	global_load_dwordx4 v[224:227], v[224:225], off
	v_add_co_u32_e32 v236, vcc, 0x81f2000, v240
	v_lshl_add_u64 v[232:233], v[78:79], 0, s[20:21]
	global_load_dwordx4 v[228:231], v[228:229], off
	v_addc_co_u32_e32 v237, vcc, 0, v241, vcc
	global_load_dwordx4 v[232:235], v[232:233], off
	v_add_co_u32_e32 v240, vcc, 0x822e000, v240
	global_load_dwordx4 v[236:239], v[236:237], off offset:512
	s_nop 0
	v_addc_co_u32_e32 v241, vcc, 0, v241, vcc
	global_load_dwordx4 v[240:243], v[240:241], off offset:1536
	s_add_i32 s2, s2, 1
	s_waitcnt lgkmcnt(0)
	s_barrier
	s_mov_b64 s[40:41], 0x18000
	v_add_u32_e32 v72, 64, v72
	v_add_u32_e32 v74, 64, v74
	v_lshl_add_u64 v[76:77], v[76:77], 0, s[76:77]
	v_lshl_add_u64 v[78:79], v[78:79], 0, s[76:77]
	v_lshl_add_u64 v[80:81], v[80:81], 0, s[76:77]
	v_lshl_add_u64 v[82:83], v[82:83], 0, s[76:77]
	v_lshl_add_u64 v[84:85], v[84:85], 0, s[76:77]
	v_lshl_add_u64 v[86:87], v[86:87], 0, s[76:77]
	v_lshl_add_u64 v[88:89], v[88:89], 0, s[40:41]
	s_waitcnt vmcnt(18)
	ds_write_b128 v91, v[2:5]
	ds_write_b128 v91, v[10:13] offset:17408
	ds_write_b128 v91, v[14:17] offset:34816
	ds_write_b128 v92, v[6:9] offset:52224
	ds_write_b128 v91, v[18:21] offset:4352
	ds_write_b128 v91, v[26:29] offset:21760
	ds_write_b128 v91, v[30:33] offset:39168
	ds_write_b128 v93, v[22:25] offset:52224
	ds_write_b128 v91, v[34:37] offset:8704
	ds_write_b128 v91, v[42:45] offset:26112
	ds_write_b128 v91, v[46:49] offset:43520
	ds_write_b128 v94, v[38:41] offset:52224
	ds_write_b128 v91, v[50:53] offset:13056
	ds_write_b128 v91, v[58:61] offset:30464
	ds_write_b128 v91, v[62:65] offset:47872
	ds_write_b128 v95, v[54:57] offset:52224
	ds_write_b128 v96, v[98:101]
	ds_write_b128 v96, v[102:105] offset:4608
	s_branch .Lgp_even
; #define LDS_BARRIER() do { asm volatile("s_waitcnt lgkmcnt(0)" ::: "memory"); __builtin_amdgcn_s_barrier(); asm volatile("" ::: "memory"); } while (0)
; #define GDN_STORE_O(nn) do { const LAS bf16_t* ob_ = OTb + ((nn) & 1) * 4608; _Pragma("unroll") for (int k_ = 0; k_ < 2; ++k_) { const int vi_ = pt_ + 256 * k_, row_ = vi_ >> 3, c8_ = (vi_ & 7) * 8; \
;             *(u32x4*)(Y + (size_t)(b * T_ + 64 * (nn) + row_) * D_ + 256 + h * 128 + 64 * dvh + c8_) = *(const LAS u32x4*)(ob_ + row_ * 72 + c8_); } } while (0)
; __device__ __forceinline__ void gdn_scan(const Ctx& c, const Params& p, int e) {
;     ...
;             LDS_BARRIER();
;             GDN_STORE_O(127);
.Lgp_done:
	s_or_b32 s2, s4, 0x1f80
	v_add_u32_e32 v6, s2, v68
	s_waitcnt lgkmcnt(0)
	s_barrier
	v_add_u32_e32 v2, v69, v90
	v_ashrrev_i32_e32 v7, 31, v6
	ds_read_b128 v[2:5], v2
	v_lshlrev_b64 v[6:7], 11, v[6:7]
	v_lshl_add_u64 v[6:7], s[74:75], 0, v[6:7]
	v_lshl_add_u64 v[6:7], v[6:7], 0, s[20:21]
	s_lshl_b32 s42, s34, 1
	v_lshl_add_u64 v[6:7], v[6:7], 0, s[42:43]
	v_lshlrev_b32_e32 v8, 1, v66
	v_mov_b32_e32 v9, v0
	v_lshl_add_u64 v[6:7], v[6:7], 0, v[8:9]
	s_waitcnt lgkmcnt(0)
	global_store_dwordx4 v[6:7], v[2:5], off offset:512
	v_add_u32_e32 v6, s2, v1
	v_ashrrev_i32_e32 v7, 31, v6
	v_add_u32_e32 v2, v69, v67
	ds_read_b128 v[2:5], v2
	v_lshlrev_b64 v[6:7], 11, v[6:7]
	v_lshl_add_u64 v[6:7], s[74:75], 0, v[6:7]
	v_lshl_add_u64 v[6:7], v[6:7], 0, s[20:21]
	v_lshl_add_u64 v[6:7], v[6:7], 0, s[42:43]
	v_lshl_add_u64 v[6:7], v[6:7], 0, v[8:9]
	s_waitcnt lgkmcnt(0)
	global_store_dwordx4 v[6:7], v[2:5], off offset:512
	s_or_b32 s2, s4, 0x1fc0
	s_waitcnt lgkmcnt(0)
	s_barrier
	v_add_u32_e32 v10, s26, v8
	v_add_u32_e32 v6, s2, v68
	s_waitcnt lgkmcnt(0)
	s_barrier
	v_add_u32_e32 v2, v10, v90
	v_ashrrev_i32_e32 v7, 31, v6
	ds_read_b128 v[2:5], v2
	v_lshlrev_b64 v[6:7], 11, v[6:7]
	v_lshl_add_u64 v[6:7], s[74:75], 0, v[6:7]
	v_lshl_add_u64 v[6:7], v[6:7], 0, s[20:21]
	v_lshl_add_u64 v[6:7], v[6:7], 0, s[42:43]
	v_lshl_add_u64 v[6:7], v[6:7], 0, v[8:9]
	s_waitcnt lgkmcnt(0)
	global_store_dwordx4 v[6:7], v[2:5], off offset:512
	v_add_u32_e32 v6, s2, v1
	v_ashrrev_i32_e32 v7, 31, v6
	v_add_u32_e32 v2, v10, v67
	ds_read_b128 v[2:5], v2
	v_lshlrev_b64 v[6:7], 11, v[6:7]
	v_lshl_add_u64 v[6:7], s[74:75], 0, v[6:7]
	v_lshl_add_u64 v[6:7], v[6:7], 0, s[20:21]
	v_lshl_add_u64 v[6:7], v[6:7], 0, s[42:43]
	v_lshl_add_u64 v[6:7], v[6:7], 0, v[8:9]
	v_readlane_b32 s41, v255, 14
	s_waitcnt lgkmcnt(0)
	global_store_dwordx4 v[6:7], v[2:5], off offset:512
	s_branch .LBB0_521
